# epilogue: half-1 base loads issued as half-0 quads are consumed (one exposed round trip)
# speedup vs baseline: 1.0122x; 1.0035x over previous
;     __device__ __forceinline__ void operator()(const f32x4 (&acc)[2][2][4][2], const Unit& u, int wr, int wc, int fr, int fq) const {
;         const int row0 = u.pm * BM + wr * 64 + fr, col0 = u.pn * BM + wc * 32 + 8 * fq;
; #pragma unroll
;         for (int ai = 0; ai < 2; ++ai)
; #pragma unroll
;             for (int m = 0; m < 4; ++m) { const size_t ro = (size_t)(row0 + ai * HALF + m * 16) * ldc + col0;
; #pragma unroll
;                 for (int bj = 0; bj < 2; ++bj) {
;                     const f32x4 b0 = *(const f32x4*)(base + ro + bj * HALF), b1 = *(const f32x4*)(base + ro + bj * HALF + 4);
;                     *(f32x4*)(out + ro + bj * HALF) = b0 + acc[ai][bj][m][0] * scale;
;                     *(f32x4*)(out + ro + bj * HALF + 4) = b1 + acc[ai][bj][m][1] * scale; } }
.LBB0_182:
	v_lshl_add_u32 v219, s68, 8, v146
	v_lshl_or_b32 v220, s69, 8, v148
	v_lshlrev_b32_e32 v219, 13, v219
	v_lshl_add_u32 v218, v220, 2, v219
	s_and_b64 vcc, exec, s[4:5]
	s_mov_b64 s[4:5], -1
	v_add_u32_e32 v219, 0x0, v218
	global_load_dwordx4 v[152:155], v219, s[16:17]
	global_load_dwordx4 v[156:159], v219, s[16:17] offset:16
	global_load_dwordx4 v[160:163], v219, s[16:17] offset:512
	global_load_dwordx4 v[164:167], v219, s[16:17] offset:528
	v_add_u32_e32 v220, 0x20000, v218
	global_load_dwordx4 v[168:171], v220, s[16:17]
	global_load_dwordx4 v[172:175], v220, s[16:17] offset:16
	global_load_dwordx4 v[176:179], v220, s[16:17] offset:512
	global_load_dwordx4 v[180:183], v220, s[16:17] offset:528
	v_add_u32_e32 v219, 0x40000, v218
	global_load_dwordx4 v[186:189], v219, s[16:17]
	global_load_dwordx4 v[190:193], v219, s[16:17] offset:16
	global_load_dwordx4 v[194:197], v219, s[16:17] offset:512
	global_load_dwordx4 v[198:201], v219, s[16:17] offset:528
	v_add_u32_e32 v220, 0x60000, v218
	global_load_dwordx4 v[202:205], v220, s[16:17]
	global_load_dwordx4 v[206:209], v220, s[16:17] offset:16
	global_load_dwordx4 v[210:213], v220, s[16:17] offset:512
	global_load_dwordx4 v[214:217], v220, s[16:17] offset:528
	v_add_u32_e32 v219, 0x100000, v218
	s_waitcnt vmcnt(15)
	v_pk_fma_f32 v[124:125], v[124:125], 0.5, v[152:153] op_sel_hi:[1,0,1]
	v_pk_fma_f32 v[126:127], v[126:127], 0.5, v[154:155] op_sel_hi:[1,0,1]
	global_load_dwordx4 v[152:155], v219, s[16:17]
	s_waitcnt vmcnt(15)
	v_pk_fma_f32 v[120:121], v[120:121], 0.5, v[156:157] op_sel_hi:[1,0,1]
	v_pk_fma_f32 v[122:123], v[122:123], 0.5, v[158:159] op_sel_hi:[1,0,1]
	global_load_dwordx4 v[156:159], v219, s[16:17] offset:16
	s_waitcnt vmcnt(15)
	v_pk_fma_f32 v[112:113], v[112:113], 0.5, v[160:161] op_sel_hi:[1,0,1]
	v_pk_fma_f32 v[114:115], v[114:115], 0.5, v[162:163] op_sel_hi:[1,0,1]
	global_load_dwordx4 v[160:163], v219, s[16:17] offset:512
	s_waitcnt vmcnt(15)
	v_pk_fma_f32 v[108:109], v[108:109], 0.5, v[164:165] op_sel_hi:[1,0,1]
	v_pk_fma_f32 v[110:111], v[110:111], 0.5, v[166:167] op_sel_hi:[1,0,1]
	global_load_dwordx4 v[164:167], v219, s[16:17] offset:528
	v_add_u32_e32 v220, 0x120000, v218
	s_waitcnt vmcnt(15)
	v_pk_fma_f32 v[116:117], v[116:117], 0.5, v[168:169] op_sel_hi:[1,0,1]
	v_pk_fma_f32 v[118:119], v[118:119], 0.5, v[170:171] op_sel_hi:[1,0,1]
	global_load_dwordx4 v[168:171], v220, s[16:17]
	s_waitcnt vmcnt(15)
	v_pk_fma_f32 v[104:105], v[104:105], 0.5, v[172:173] op_sel_hi:[1,0,1]
	v_pk_fma_f32 v[106:107], v[106:107], 0.5, v[174:175] op_sel_hi:[1,0,1]
	global_load_dwordx4 v[172:175], v220, s[16:17] offset:16
	s_waitcnt vmcnt(15)
	v_pk_fma_f32 v[96:97], v[96:97], 0.5, v[176:177] op_sel_hi:[1,0,1]
	v_pk_fma_f32 v[98:99], v[98:99], 0.5, v[178:179] op_sel_hi:[1,0,1]
	global_load_dwordx4 v[176:179], v220, s[16:17] offset:512
	s_waitcnt vmcnt(15)
	v_pk_fma_f32 v[92:93], v[92:93], 0.5, v[180:181] op_sel_hi:[1,0,1]
	v_pk_fma_f32 v[94:95], v[94:95], 0.5, v[182:183] op_sel_hi:[1,0,1]
	global_load_dwordx4 v[180:183], v220, s[16:17] offset:528
	v_add_u32_e32 v219, 0x140000, v218
	s_waitcnt vmcnt(15)
	v_pk_fma_f32 v[100:101], v[100:101], 0.5, v[186:187] op_sel_hi:[1,0,1]
	v_pk_fma_f32 v[102:103], v[102:103], 0.5, v[188:189] op_sel_hi:[1,0,1]
	global_load_dwordx4 v[186:189], v219, s[16:17]
	s_waitcnt vmcnt(15)
	v_pk_fma_f32 v[88:89], v[88:89], 0.5, v[190:191] op_sel_hi:[1,0,1]
	v_pk_fma_f32 v[90:91], v[90:91], 0.5, v[192:193] op_sel_hi:[1,0,1]
	global_load_dwordx4 v[190:193], v219, s[16:17] offset:16
	s_waitcnt vmcnt(15)
	v_pk_fma_f32 v[80:81], v[80:81], 0.5, v[194:195] op_sel_hi:[1,0,1]
	v_pk_fma_f32 v[82:83], v[82:83], 0.5, v[196:197] op_sel_hi:[1,0,1]
	global_load_dwordx4 v[194:197], v219, s[16:17] offset:512
	s_waitcnt vmcnt(15)
	v_pk_fma_f32 v[76:77], v[76:77], 0.5, v[198:199] op_sel_hi:[1,0,1]
	v_pk_fma_f32 v[78:79], v[78:79], 0.5, v[200:201] op_sel_hi:[1,0,1]
	global_load_dwordx4 v[198:201], v219, s[16:17] offset:528
	v_add_u32_e32 v220, 0x160000, v218
	s_waitcnt vmcnt(15)
	v_pk_fma_f32 v[84:85], v[84:85], 0.5, v[202:203] op_sel_hi:[1,0,1]
	v_pk_fma_f32 v[86:87], v[86:87], 0.5, v[204:205] op_sel_hi:[1,0,1]
	global_load_dwordx4 v[202:205], v220, s[16:17]
	s_waitcnt vmcnt(15)
	v_pk_fma_f32 v[72:73], v[72:73], 0.5, v[206:207] op_sel_hi:[1,0,1]
	v_pk_fma_f32 v[74:75], v[74:75], 0.5, v[208:209] op_sel_hi:[1,0,1]
	global_load_dwordx4 v[206:209], v220, s[16:17] offset:16
	s_waitcnt vmcnt(15)
	v_pk_fma_f32 v[68:69], v[68:69], 0.5, v[210:211] op_sel_hi:[1,0,1]
	v_pk_fma_f32 v[70:71], v[70:71], 0.5, v[212:213] op_sel_hi:[1,0,1]
	global_load_dwordx4 v[210:213], v220, s[16:17] offset:512
	s_waitcnt vmcnt(15)
;     __device__ __forceinline__ void operator()(const f32x4 (&acc)[2][2][4][2], const Unit& u, int wr, int wc, int fr, int fq) const {
;         const int row0 = u.pm * BM + wr * 64 + fr, col0 = u.pn * BM + wc * 32 + 8 * fq;
; #pragma unroll
;         for (int ai = 0; ai < 2; ++ai)
; #pragma unroll
;             for (int m = 0; m < 4; ++m) { const size_t ro = (size_t)(row0 + ai * HALF + m * 16) * ldc + col0;
; #pragma unroll
;                 for (int bj = 0; bj < 2; ++bj) {
;                     const f32x4 b0 = *(const f32x4*)(base + ro + bj * HALF), b1 = *(const f32x4*)(base + ro + bj * HALF + 4);
;                     *(f32x4*)(out + ro + bj * HALF) = b0 + acc[ai][bj][m][0] * scale;
;                     *(f32x4*)(out + ro + bj * HALF + 4) = b1 + acc[ai][bj][m][1] * scale; } }
	v_pk_fma_f32 v[64:65], v[64:65], 0.5, v[214:215] op_sel_hi:[1,0,1]
	v_pk_fma_f32 v[66:67], v[66:67], 0.5, v[216:217] op_sel_hi:[1,0,1]
	global_load_dwordx4 v[214:217], v220, s[16:17] offset:528
	v_add_u32_e32 v219, 0x0, v218
	global_store_dwordx4 v219, v[124:127], s[18:19]
	global_store_dwordx4 v219, v[120:123], s[18:19] offset:16
	global_store_dwordx4 v219, v[112:115], s[18:19] offset:512
	global_store_dwordx4 v219, v[108:111], s[18:19] offset:528
	v_add_u32_e32 v220, 0x20000, v218
	global_store_dwordx4 v220, v[116:119], s[18:19]
	global_store_dwordx4 v220, v[104:107], s[18:19] offset:16
	global_store_dwordx4 v220, v[96:99], s[18:19] offset:512
	global_store_dwordx4 v220, v[92:95], s[18:19] offset:528
	v_add_u32_e32 v219, 0x40000, v218
	global_store_dwordx4 v219, v[100:103], s[18:19]
	global_store_dwordx4 v219, v[88:91], s[18:19] offset:16
	global_store_dwordx4 v219, v[80:83], s[18:19] offset:512
	global_store_dwordx4 v219, v[76:79], s[18:19] offset:528
	v_add_u32_e32 v220, 0x60000, v218
	global_store_dwordx4 v220, v[84:87], s[18:19]
	global_store_dwordx4 v220, v[72:75], s[18:19] offset:16
	global_store_dwordx4 v220, v[68:71], s[18:19] offset:512
	global_store_dwordx4 v220, v[64:67], s[18:19] offset:528
	s_waitcnt vmcnt(31)
	v_pk_fma_f32 v[60:61], v[60:61], 0.5, v[152:153] op_sel_hi:[1,0,1]
	v_pk_fma_f32 v[62:63], v[62:63], 0.5, v[154:155] op_sel_hi:[1,0,1]
	s_waitcnt vmcnt(30)
	v_pk_fma_f32 v[56:57], v[56:57], 0.5, v[156:157] op_sel_hi:[1,0,1]
	v_pk_fma_f32 v[58:59], v[58:59], 0.5, v[158:159] op_sel_hi:[1,0,1]
	s_waitcnt vmcnt(29)
	v_pk_fma_f32 v[48:49], v[48:49], 0.5, v[160:161] op_sel_hi:[1,0,1]
	v_pk_fma_f32 v[50:51], v[50:51], 0.5, v[162:163] op_sel_hi:[1,0,1]
	s_waitcnt vmcnt(28)
	v_pk_fma_f32 v[44:45], v[44:45], 0.5, v[164:165] op_sel_hi:[1,0,1]
	v_pk_fma_f32 v[46:47], v[46:47], 0.5, v[166:167] op_sel_hi:[1,0,1]
	s_waitcnt vmcnt(27)
	v_pk_fma_f32 v[52:53], v[52:53], 0.5, v[168:169] op_sel_hi:[1,0,1]
	v_pk_fma_f32 v[54:55], v[54:55], 0.5, v[170:171] op_sel_hi:[1,0,1]
	s_waitcnt vmcnt(26)
	v_pk_fma_f32 v[40:41], v[40:41], 0.5, v[172:173] op_sel_hi:[1,0,1]
	v_pk_fma_f32 v[42:43], v[42:43], 0.5, v[174:175] op_sel_hi:[1,0,1]
	s_waitcnt vmcnt(25)
	v_pk_fma_f32 v[32:33], v[32:33], 0.5, v[176:177] op_sel_hi:[1,0,1]
	v_pk_fma_f32 v[34:35], v[34:35], 0.5, v[178:179] op_sel_hi:[1,0,1]
	s_waitcnt vmcnt(24)
	v_pk_fma_f32 v[28:29], v[28:29], 0.5, v[180:181] op_sel_hi:[1,0,1]
	v_pk_fma_f32 v[30:31], v[30:31], 0.5, v[182:183] op_sel_hi:[1,0,1]
	s_waitcnt vmcnt(23)
	v_pk_fma_f32 v[36:37], v[36:37], 0.5, v[186:187] op_sel_hi:[1,0,1]
	v_pk_fma_f32 v[38:39], v[38:39], 0.5, v[188:189] op_sel_hi:[1,0,1]
	s_waitcnt vmcnt(22)
	v_pk_fma_f32 v[24:25], v[24:25], 0.5, v[190:191] op_sel_hi:[1,0,1]
	v_pk_fma_f32 v[26:27], v[26:27], 0.5, v[192:193] op_sel_hi:[1,0,1]
	s_waitcnt vmcnt(21)
	v_pk_fma_f32 v[16:17], v[16:17], 0.5, v[194:195] op_sel_hi:[1,0,1]
	v_pk_fma_f32 v[18:19], v[18:19], 0.5, v[196:197] op_sel_hi:[1,0,1]
	s_waitcnt vmcnt(20)
	v_pk_fma_f32 v[12:13], v[12:13], 0.5, v[198:199] op_sel_hi:[1,0,1]
	v_pk_fma_f32 v[14:15], v[14:15], 0.5, v[200:201] op_sel_hi:[1,0,1]
	s_waitcnt vmcnt(19)
	v_pk_fma_f32 v[20:21], v[20:21], 0.5, v[202:203] op_sel_hi:[1,0,1]
	v_pk_fma_f32 v[22:23], v[22:23], 0.5, v[204:205] op_sel_hi:[1,0,1]
	s_waitcnt vmcnt(18)
	v_pk_fma_f32 v[8:9], v[8:9], 0.5, v[206:207] op_sel_hi:[1,0,1]
	v_pk_fma_f32 v[10:11], v[10:11], 0.5, v[208:209] op_sel_hi:[1,0,1]
	s_waitcnt vmcnt(17)
	v_pk_fma_f32 v[4:5], v[4:5], 0.5, v[210:211] op_sel_hi:[1,0,1]
	v_pk_fma_f32 v[6:7], v[6:7], 0.5, v[212:213] op_sel_hi:[1,0,1]
	s_waitcnt vmcnt(16)
	v_pk_fma_f32 v[0:1], v[0:1], 0.5, v[214:215] op_sel_hi:[1,0,1]
	v_pk_fma_f32 v[2:3], v[2:3], 0.5, v[216:217] op_sel_hi:[1,0,1]
	v_add_u32_e32 v219, 0x100000, v218
	global_store_dwordx4 v219, v[60:63], s[18:19]
	global_store_dwordx4 v219, v[56:59], s[18:19] offset:16
	global_store_dwordx4 v219, v[48:51], s[18:19] offset:512
	global_store_dwordx4 v219, v[44:47], s[18:19] offset:528
	v_add_u32_e32 v220, 0x120000, v218
	global_store_dwordx4 v220, v[52:55], s[18:19]
	global_store_dwordx4 v220, v[40:43], s[18:19] offset:16
	global_store_dwordx4 v220, v[32:35], s[18:19] offset:512
	global_store_dwordx4 v220, v[28:31], s[18:19] offset:528
	v_add_u32_e32 v219, 0x140000, v218
	global_store_dwordx4 v219, v[36:39], s[18:19]
	global_store_dwordx4 v219, v[24:27], s[18:19] offset:16
	global_store_dwordx4 v219, v[16:19], s[18:19] offset:512
	global_store_dwordx4 v219, v[12:15], s[18:19] offset:528
	v_add_u32_e32 v220, 0x160000, v218
	global_store_dwordx4 v220, v[20:23], s[18:19]
	global_store_dwordx4 v220, v[8:11], s[18:19] offset:16
	global_store_dwordx4 v220, v[4:7], s[18:19] offset:512
	global_store_dwordx4 v220, v[0:3], s[18:19] offset:528
	s_nop 1
	s_cbranch_vccnz .LBB0_167
	s_andn2_b64 vcc, exec, s[12:13]
	s_cbranch_vccnz .LBB0_166
	s_barrier
	s_branch .LBB0_166

;     __device__ __forceinline__ void operator()(const f32x4 (&acc)[2][2][4][2], const Unit& u, int wr, int wc, int fr, int fq) const {
;         const int row0 = u.pm * BM + wr * 64 + fr, col0 = u.pn * BM + wc * 32 + 8 * fq;
; #pragma unroll
;         for (int ai = 0; ai < 2; ++ai)
; #pragma unroll
;             for (int m = 0; m < 4; ++m) { const size_t ro = (size_t)(row0 + ai * HALF + m * 16) * ldc + col0;
; #pragma unroll
;                 for (int bj = 0; bj < 2; ++bj) {
;                     const f32x4 b0 = *(const f32x4*)(base + ro + bj * HALF), b1 = *(const f32x4*)(base + ro + bj * HALF + 4);
;                     *(f32x4*)(out + ro + bj * HALF) = b0 + acc[ai][bj][m][0] * scale;
;                     *(f32x4*)(out + ro + bj * HALF + 4) = b1 + acc[ai][bj][m][1] * scale; } }
.LBB0_1324:
	v_lshl_add_u32 v219, s50, 8, v150
	v_lshl_or_b32 v220, s51, 8, v152
	v_lshlrev_b32_e32 v219, 13, v219
	v_lshl_add_u32 v218, v220, 2, v219
	s_mov_b64 s[50:51], -1
	s_andn2_b64 vcc, exec, s[4:5]
	v_add_u32_e32 v219, 0x0, v218
	global_load_dwordx4 v[144:147], v219, s[12:13]
	global_load_dwordx4 v[156:159], v219, s[12:13] offset:16
	global_load_dwordx4 v[160:163], v219, s[12:13] offset:512
	global_load_dwordx4 v[164:167], v219, s[12:13] offset:528
	v_add_u32_e32 v220, 0x20000, v218
	global_load_dwordx4 v[168:171], v220, s[12:13]
	global_load_dwordx4 v[172:175], v220, s[12:13] offset:16
	global_load_dwordx4 v[176:179], v220, s[12:13] offset:512
	global_load_dwordx4 v[180:183], v220, s[12:13] offset:528
	v_add_u32_e32 v219, 0x40000, v218
	global_load_dwordx4 v[186:189], v219, s[12:13]
	global_load_dwordx4 v[190:193], v219, s[12:13] offset:16
	global_load_dwordx4 v[194:197], v219, s[12:13] offset:512
	global_load_dwordx4 v[198:201], v219, s[12:13] offset:528
	v_add_u32_e32 v220, 0x60000, v218
	global_load_dwordx4 v[202:205], v220, s[12:13]
	global_load_dwordx4 v[206:209], v220, s[12:13] offset:16
	global_load_dwordx4 v[210:213], v220, s[12:13] offset:512
	global_load_dwordx4 v[214:217], v220, s[12:13] offset:528
	v_add_u32_e32 v219, 0x100000, v218
	s_waitcnt vmcnt(15)
	v_pk_add_f32 v[124:125], v[124:125], v[144:145]
	v_pk_add_f32 v[126:127], v[126:127], v[146:147]
	global_load_dwordx4 v[144:147], v219, s[12:13]
	s_waitcnt vmcnt(15)
	v_pk_add_f32 v[120:121], v[120:121], v[156:157]
	v_pk_add_f32 v[122:123], v[122:123], v[158:159]
	global_load_dwordx4 v[156:159], v219, s[12:13] offset:16
	s_waitcnt vmcnt(15)
	v_pk_add_f32 v[116:117], v[116:117], v[160:161]
	v_pk_add_f32 v[118:119], v[118:119], v[162:163]
	global_load_dwordx4 v[160:163], v219, s[12:13] offset:512
	s_waitcnt vmcnt(15)
	v_pk_add_f32 v[112:113], v[112:113], v[164:165]
	v_pk_add_f32 v[114:115], v[114:115], v[166:167]
	global_load_dwordx4 v[164:167], v219, s[12:13] offset:528
	v_add_u32_e32 v220, 0x120000, v218
	s_waitcnt vmcnt(15)
	v_pk_add_f32 v[108:109], v[108:109], v[168:169]
	v_pk_add_f32 v[110:111], v[110:111], v[170:171]
	global_load_dwordx4 v[168:171], v220, s[12:13]
	s_waitcnt vmcnt(15)
	v_pk_add_f32 v[104:105], v[104:105], v[172:173]
	v_pk_add_f32 v[106:107], v[106:107], v[174:175]
	global_load_dwordx4 v[172:175], v220, s[12:13] offset:16
	s_waitcnt vmcnt(15)
	v_pk_add_f32 v[100:101], v[100:101], v[176:177]
	v_pk_add_f32 v[102:103], v[102:103], v[178:179]
	global_load_dwordx4 v[176:179], v220, s[12:13] offset:512
	s_waitcnt vmcnt(15)
	v_pk_add_f32 v[96:97], v[96:97], v[180:181]
	v_pk_add_f32 v[98:99], v[98:99], v[182:183]
	global_load_dwordx4 v[180:183], v220, s[12:13] offset:528
	v_add_u32_e32 v219, 0x140000, v218
	s_waitcnt vmcnt(15)
	v_pk_add_f32 v[92:93], v[92:93], v[186:187]
	v_pk_add_f32 v[94:95], v[94:95], v[188:189]
	global_load_dwordx4 v[186:189], v219, s[12:13]
	s_waitcnt vmcnt(15)
	v_pk_add_f32 v[88:89], v[88:89], v[190:191]
	v_pk_add_f32 v[90:91], v[90:91], v[192:193]
	global_load_dwordx4 v[190:193], v219, s[12:13] offset:16
	s_waitcnt vmcnt(15)
	v_pk_add_f32 v[84:85], v[84:85], v[194:195]
	v_pk_add_f32 v[86:87], v[86:87], v[196:197]
	global_load_dwordx4 v[194:197], v219, s[12:13] offset:512
	s_waitcnt vmcnt(15)
	v_pk_add_f32 v[80:81], v[80:81], v[198:199]
	v_pk_add_f32 v[82:83], v[82:83], v[200:201]
	global_load_dwordx4 v[198:201], v219, s[12:13] offset:528
	v_add_u32_e32 v220, 0x160000, v218
	s_waitcnt vmcnt(15)
	v_pk_add_f32 v[76:77], v[76:77], v[202:203]
	v_pk_add_f32 v[78:79], v[78:79], v[204:205]
	global_load_dwordx4 v[202:205], v220, s[12:13]
	s_waitcnt vmcnt(15)
	v_pk_add_f32 v[72:73], v[72:73], v[206:207]
	v_pk_add_f32 v[74:75], v[74:75], v[208:209]
	global_load_dwordx4 v[206:209], v220, s[12:13] offset:16
	s_waitcnt vmcnt(15)
	v_pk_add_f32 v[68:69], v[68:69], v[210:211]
	v_pk_add_f32 v[70:71], v[70:71], v[212:213]
	global_load_dwordx4 v[210:213], v220, s[12:13] offset:512
	s_waitcnt vmcnt(15)
;     __device__ __forceinline__ void operator()(const f32x4 (&acc)[2][2][4][2], const Unit& u, int wr, int wc, int fr, int fq) const {
;         const int row0 = u.pm * BM + wr * 64 + fr, col0 = u.pn * BM + wc * 32 + 8 * fq;
; #pragma unroll
;         for (int ai = 0; ai < 2; ++ai)
; #pragma unroll
;             for (int m = 0; m < 4; ++m) { const size_t ro = (size_t)(row0 + ai * HALF + m * 16) * ldc + col0;
; #pragma unroll
;                 for (int bj = 0; bj < 2; ++bj) {
;                     const f32x4 b0 = *(const f32x4*)(base + ro + bj * HALF), b1 = *(const f32x4*)(base + ro + bj * HALF + 4);
;                     *(f32x4*)(out + ro + bj * HALF) = b0 + acc[ai][bj][m][0] * scale;
;                     *(f32x4*)(out + ro + bj * HALF + 4) = b1 + acc[ai][bj][m][1] * scale; } }
	v_pk_add_f32 v[64:65], v[64:65], v[214:215]
	v_pk_add_f32 v[66:67], v[66:67], v[216:217]
	global_load_dwordx4 v[214:217], v220, s[12:13] offset:528
	v_add_u32_e32 v219, 0x0, v218
	global_store_dwordx4 v219, v[124:127], s[12:13]
	global_store_dwordx4 v219, v[120:123], s[12:13] offset:16
	global_store_dwordx4 v219, v[116:119], s[12:13] offset:512
	global_store_dwordx4 v219, v[112:115], s[12:13] offset:528
	v_add_u32_e32 v220, 0x20000, v218
	global_store_dwordx4 v220, v[108:111], s[12:13]
	global_store_dwordx4 v220, v[104:107], s[12:13] offset:16
	global_store_dwordx4 v220, v[100:103], s[12:13] offset:512
	global_store_dwordx4 v220, v[96:99], s[12:13] offset:528
	v_add_u32_e32 v219, 0x40000, v218
	global_store_dwordx4 v219, v[92:95], s[12:13]
	global_store_dwordx4 v219, v[88:91], s[12:13] offset:16
	global_store_dwordx4 v219, v[84:87], s[12:13] offset:512
	global_store_dwordx4 v219, v[80:83], s[12:13] offset:528
	v_add_u32_e32 v220, 0x60000, v218
	global_store_dwordx4 v220, v[76:79], s[12:13]
	global_store_dwordx4 v220, v[72:75], s[12:13] offset:16
	global_store_dwordx4 v220, v[68:71], s[12:13] offset:512
	global_store_dwordx4 v220, v[64:67], s[12:13] offset:528
	s_waitcnt vmcnt(31)
	v_pk_add_f32 v[60:61], v[60:61], v[144:145]
	v_pk_add_f32 v[62:63], v[62:63], v[146:147]
	s_waitcnt vmcnt(30)
	v_pk_add_f32 v[56:57], v[56:57], v[156:157]
	v_pk_add_f32 v[58:59], v[58:59], v[158:159]
	s_waitcnt vmcnt(29)
	v_pk_add_f32 v[52:53], v[52:53], v[160:161]
	v_pk_add_f32 v[54:55], v[54:55], v[162:163]
	s_waitcnt vmcnt(28)
	v_pk_add_f32 v[48:49], v[48:49], v[164:165]
	v_pk_add_f32 v[50:51], v[50:51], v[166:167]
	s_waitcnt vmcnt(27)
	v_pk_add_f32 v[44:45], v[44:45], v[168:169]
	v_pk_add_f32 v[46:47], v[46:47], v[170:171]
	s_waitcnt vmcnt(26)
	v_pk_add_f32 v[40:41], v[40:41], v[172:173]
	v_pk_add_f32 v[42:43], v[42:43], v[174:175]
	s_waitcnt vmcnt(25)
	v_pk_add_f32 v[36:37], v[36:37], v[176:177]
	v_pk_add_f32 v[38:39], v[38:39], v[178:179]
	s_waitcnt vmcnt(24)
	v_pk_add_f32 v[32:33], v[32:33], v[180:181]
	v_pk_add_f32 v[34:35], v[34:35], v[182:183]
	s_waitcnt vmcnt(23)
	v_pk_add_f32 v[28:29], v[28:29], v[186:187]
	v_pk_add_f32 v[30:31], v[30:31], v[188:189]
	s_waitcnt vmcnt(22)
	v_pk_add_f32 v[24:25], v[24:25], v[190:191]
	v_pk_add_f32 v[26:27], v[26:27], v[192:193]
	s_waitcnt vmcnt(21)
	v_pk_add_f32 v[20:21], v[20:21], v[194:195]
	v_pk_add_f32 v[22:23], v[22:23], v[196:197]
	s_waitcnt vmcnt(20)
	v_pk_add_f32 v[16:17], v[16:17], v[198:199]
	v_pk_add_f32 v[18:19], v[18:19], v[200:201]
	s_waitcnt vmcnt(19)
	v_pk_add_f32 v[12:13], v[12:13], v[202:203]
	v_pk_add_f32 v[14:15], v[14:15], v[204:205]
	s_waitcnt vmcnt(18)
	v_pk_add_f32 v[8:9], v[8:9], v[206:207]
	v_pk_add_f32 v[10:11], v[10:11], v[208:209]
	s_waitcnt vmcnt(17)
	v_pk_add_f32 v[4:5], v[4:5], v[210:211]
	v_pk_add_f32 v[6:7], v[6:7], v[212:213]
	s_waitcnt vmcnt(16)
	v_pk_add_f32 v[0:1], v[0:1], v[214:215]
	v_pk_add_f32 v[2:3], v[2:3], v[216:217]
	v_add_u32_e32 v219, 0x100000, v218
	global_store_dwordx4 v219, v[60:63], s[12:13]
	global_store_dwordx4 v219, v[56:59], s[12:13] offset:16
	global_store_dwordx4 v219, v[52:55], s[12:13] offset:512
	global_store_dwordx4 v219, v[48:51], s[12:13] offset:528
	v_add_u32_e32 v220, 0x120000, v218
	global_store_dwordx4 v220, v[44:47], s[12:13]
	global_store_dwordx4 v220, v[40:43], s[12:13] offset:16
	global_store_dwordx4 v220, v[36:39], s[12:13] offset:512
	global_store_dwordx4 v220, v[32:35], s[12:13] offset:528
	v_add_u32_e32 v219, 0x140000, v218
	global_store_dwordx4 v219, v[28:31], s[12:13]
	global_store_dwordx4 v219, v[24:27], s[12:13] offset:16
	global_store_dwordx4 v219, v[20:23], s[12:13] offset:512
	global_store_dwordx4 v219, v[16:19], s[12:13] offset:528
	v_add_u32_e32 v220, 0x160000, v218
	global_store_dwordx4 v220, v[12:15], s[12:13]
	global_store_dwordx4 v220, v[8:11], s[12:13] offset:16
	global_store_dwordx4 v220, v[4:7], s[12:13] offset:512
	global_store_dwordx4 v220, v[0:3], s[12:13] offset:528
	s_nop 1
	s_cbranch_vccnz .LBB0_1313
	s_andn2_b64 vcc, exec, s[8:9]
	s_cbranch_vccnz .LBB0_1312
	s_barrier
	s_branch .LBB0_1312

;     __device__ __forceinline__ void operator()(const f32x4 (&acc)[2][2][4][2], const Unit& u, int wr, int wc, int fr, int fq) const {
;         const int row0 = u.pm * BM + wr * 64 + fr, col0 = u.pn * BM + wc * 32 + 8 * fq;
; #pragma unroll
;         for (int ai = 0; ai < 2; ++ai)
; #pragma unroll
;             for (int m = 0; m < 4; ++m) { const size_t ro = (size_t)(row0 + ai * HALF + m * 16) * ldc + col0;
; #pragma unroll
;                 for (int bj = 0; bj < 2; ++bj) {
;                     const f32x4 b0 = *(const f32x4*)(base + ro + bj * HALF), b1 = *(const f32x4*)(base + ro + bj * HALF + 4);
;                     *(f32x4*)(out + ro + bj * HALF) = b0 + acc[ai][bj][m][0] * scale;
;                     *(f32x4*)(out + ro + bj * HALF + 4) = b1 + acc[ai][bj][m][1] * scale; } }
.LBB0_1542:
	v_lshl_add_u32 v219, s64, 8, v150
	v_lshl_or_b32 v220, s65, 8, v152
	v_lshlrev_b32_e32 v219, 13, v219
	v_lshl_add_u32 v218, v220, 2, v219
	s_mov_b64 s[40:41], -1
	s_and_b64 vcc, exec, s[4:5]
	v_add_u32_e32 v219, 0x0, v218
	global_load_dwordx4 v[144:147], v219, s[16:17]
	global_load_dwordx4 v[156:159], v219, s[16:17] offset:16
	global_load_dwordx4 v[160:163], v219, s[16:17] offset:512
	global_load_dwordx4 v[164:167], v219, s[16:17] offset:528
	v_add_u32_e32 v220, 0x20000, v218
	global_load_dwordx4 v[168:171], v220, s[16:17]
	global_load_dwordx4 v[172:175], v220, s[16:17] offset:16
	global_load_dwordx4 v[176:179], v220, s[16:17] offset:512
	global_load_dwordx4 v[180:183], v220, s[16:17] offset:528
	v_add_u32_e32 v219, 0x40000, v218
	global_load_dwordx4 v[186:189], v219, s[16:17]
	global_load_dwordx4 v[190:193], v219, s[16:17] offset:16
	global_load_dwordx4 v[194:197], v219, s[16:17] offset:512
	global_load_dwordx4 v[198:201], v219, s[16:17] offset:528
	v_add_u32_e32 v220, 0x60000, v218
	global_load_dwordx4 v[202:205], v220, s[16:17]
	global_load_dwordx4 v[206:209], v220, s[16:17] offset:16
	global_load_dwordx4 v[210:213], v220, s[16:17] offset:512
	global_load_dwordx4 v[214:217], v220, s[16:17] offset:528
	v_add_u32_e32 v219, 0x100000, v218
	s_waitcnt vmcnt(15)
	v_pk_fma_f32 v[124:125], v[124:125], 0.5, v[144:145] op_sel_hi:[1,0,1]
	v_pk_fma_f32 v[126:127], v[126:127], 0.5, v[146:147] op_sel_hi:[1,0,1]
	global_load_dwordx4 v[144:147], v219, s[16:17]
	s_waitcnt vmcnt(15)
	v_pk_fma_f32 v[120:121], v[120:121], 0.5, v[156:157] op_sel_hi:[1,0,1]
	v_pk_fma_f32 v[122:123], v[122:123], 0.5, v[158:159] op_sel_hi:[1,0,1]
	global_load_dwordx4 v[156:159], v219, s[16:17] offset:16
	s_waitcnt vmcnt(15)
	v_pk_fma_f32 v[116:117], v[116:117], 0.5, v[160:161] op_sel_hi:[1,0,1]
	v_pk_fma_f32 v[118:119], v[118:119], 0.5, v[162:163] op_sel_hi:[1,0,1]
	global_load_dwordx4 v[160:163], v219, s[16:17] offset:512
	s_waitcnt vmcnt(15)
	v_pk_fma_f32 v[112:113], v[112:113], 0.5, v[164:165] op_sel_hi:[1,0,1]
	v_pk_fma_f32 v[114:115], v[114:115], 0.5, v[166:167] op_sel_hi:[1,0,1]
	global_load_dwordx4 v[164:167], v219, s[16:17] offset:528
	v_add_u32_e32 v220, 0x120000, v218
	s_waitcnt vmcnt(15)
	v_pk_fma_f32 v[108:109], v[108:109], 0.5, v[168:169] op_sel_hi:[1,0,1]
	v_pk_fma_f32 v[110:111], v[110:111], 0.5, v[170:171] op_sel_hi:[1,0,1]
	global_load_dwordx4 v[168:171], v220, s[16:17]
	s_waitcnt vmcnt(15)
	v_pk_fma_f32 v[104:105], v[104:105], 0.5, v[172:173] op_sel_hi:[1,0,1]
	v_pk_fma_f32 v[106:107], v[106:107], 0.5, v[174:175] op_sel_hi:[1,0,1]
	global_load_dwordx4 v[172:175], v220, s[16:17] offset:16
	s_waitcnt vmcnt(15)
	v_pk_fma_f32 v[100:101], v[100:101], 0.5, v[176:177] op_sel_hi:[1,0,1]
	v_pk_fma_f32 v[102:103], v[102:103], 0.5, v[178:179] op_sel_hi:[1,0,1]
	global_load_dwordx4 v[176:179], v220, s[16:17] offset:512
	s_waitcnt vmcnt(15)
	v_pk_fma_f32 v[96:97], v[96:97], 0.5, v[180:181] op_sel_hi:[1,0,1]
	v_pk_fma_f32 v[98:99], v[98:99], 0.5, v[182:183] op_sel_hi:[1,0,1]
	global_load_dwordx4 v[180:183], v220, s[16:17] offset:528
	v_add_u32_e32 v219, 0x140000, v218
	s_waitcnt vmcnt(15)
	v_pk_fma_f32 v[92:93], v[92:93], 0.5, v[186:187] op_sel_hi:[1,0,1]
	v_pk_fma_f32 v[94:95], v[94:95], 0.5, v[188:189] op_sel_hi:[1,0,1]
	global_load_dwordx4 v[186:189], v219, s[16:17]
	s_waitcnt vmcnt(15)
	v_pk_fma_f32 v[88:89], v[88:89], 0.5, v[190:191] op_sel_hi:[1,0,1]
	v_pk_fma_f32 v[90:91], v[90:91], 0.5, v[192:193] op_sel_hi:[1,0,1]
	global_load_dwordx4 v[190:193], v219, s[16:17] offset:16
	s_waitcnt vmcnt(15)
	v_pk_fma_f32 v[84:85], v[84:85], 0.5, v[194:195] op_sel_hi:[1,0,1]
	v_pk_fma_f32 v[86:87], v[86:87], 0.5, v[196:197] op_sel_hi:[1,0,1]
	global_load_dwordx4 v[194:197], v219, s[16:17] offset:512
	s_waitcnt vmcnt(15)
	v_pk_fma_f32 v[80:81], v[80:81], 0.5, v[198:199] op_sel_hi:[1,0,1]
	v_pk_fma_f32 v[82:83], v[82:83], 0.5, v[200:201] op_sel_hi:[1,0,1]
	global_load_dwordx4 v[198:201], v219, s[16:17] offset:528
	v_add_u32_e32 v220, 0x160000, v218
	s_waitcnt vmcnt(15)
	v_pk_fma_f32 v[76:77], v[76:77], 0.5, v[202:203] op_sel_hi:[1,0,1]
	v_pk_fma_f32 v[78:79], v[78:79], 0.5, v[204:205] op_sel_hi:[1,0,1]
	global_load_dwordx4 v[202:205], v220, s[16:17]
	s_waitcnt vmcnt(15)
	v_pk_fma_f32 v[72:73], v[72:73], 0.5, v[206:207] op_sel_hi:[1,0,1]
	v_pk_fma_f32 v[74:75], v[74:75], 0.5, v[208:209] op_sel_hi:[1,0,1]
	global_load_dwordx4 v[206:209], v220, s[16:17] offset:16
	s_waitcnt vmcnt(15)
	v_pk_fma_f32 v[68:69], v[68:69], 0.5, v[210:211] op_sel_hi:[1,0,1]
	v_pk_fma_f32 v[70:71], v[70:71], 0.5, v[212:213] op_sel_hi:[1,0,1]
	global_load_dwordx4 v[210:213], v220, s[16:17] offset:512
	s_waitcnt vmcnt(15)
;     __device__ __forceinline__ void operator()(const f32x4 (&acc)[2][2][4][2], const Unit& u, int wr, int wc, int fr, int fq) const {
;         const int row0 = u.pm * BM + wr * 64 + fr, col0 = u.pn * BM + wc * 32 + 8 * fq;
; #pragma unroll
;         for (int ai = 0; ai < 2; ++ai)
; #pragma unroll
;             for (int m = 0; m < 4; ++m) { const size_t ro = (size_t)(row0 + ai * HALF + m * 16) * ldc + col0;
; #pragma unroll
;                 for (int bj = 0; bj < 2; ++bj) {
;                     const f32x4 b0 = *(const f32x4*)(base + ro + bj * HALF), b1 = *(const f32x4*)(base + ro + bj * HALF + 4);
;                     *(f32x4*)(out + ro + bj * HALF) = b0 + acc[ai][bj][m][0] * scale;
;                     *(f32x4*)(out + ro + bj * HALF + 4) = b1 + acc[ai][bj][m][1] * scale; } }
	v_pk_fma_f32 v[64:65], v[64:65], 0.5, v[214:215] op_sel_hi:[1,0,1]
	v_pk_fma_f32 v[66:67], v[66:67], 0.5, v[216:217] op_sel_hi:[1,0,1]
	global_load_dwordx4 v[214:217], v220, s[16:17] offset:528
	v_add_u32_e32 v219, 0x0, v218
	global_store_dwordx4 v219, v[124:127], s[16:17]
	global_store_dwordx4 v219, v[120:123], s[16:17] offset:16
	global_store_dwordx4 v219, v[116:119], s[16:17] offset:512
	global_store_dwordx4 v219, v[112:115], s[16:17] offset:528
	v_add_u32_e32 v220, 0x20000, v218
	global_store_dwordx4 v220, v[108:111], s[16:17]
	global_store_dwordx4 v220, v[104:107], s[16:17] offset:16
	global_store_dwordx4 v220, v[100:103], s[16:17] offset:512
	global_store_dwordx4 v220, v[96:99], s[16:17] offset:528
	v_add_u32_e32 v219, 0x40000, v218
	global_store_dwordx4 v219, v[92:95], s[16:17]
	global_store_dwordx4 v219, v[88:91], s[16:17] offset:16
	global_store_dwordx4 v219, v[84:87], s[16:17] offset:512
	global_store_dwordx4 v219, v[80:83], s[16:17] offset:528
	v_add_u32_e32 v220, 0x60000, v218
	global_store_dwordx4 v220, v[76:79], s[16:17]
	global_store_dwordx4 v220, v[72:75], s[16:17] offset:16
	global_store_dwordx4 v220, v[68:71], s[16:17] offset:512
	global_store_dwordx4 v220, v[64:67], s[16:17] offset:528
	s_waitcnt vmcnt(31)
	v_pk_fma_f32 v[60:61], v[60:61], 0.5, v[144:145] op_sel_hi:[1,0,1]
	v_pk_fma_f32 v[62:63], v[62:63], 0.5, v[146:147] op_sel_hi:[1,0,1]
	s_waitcnt vmcnt(30)
	v_pk_fma_f32 v[56:57], v[56:57], 0.5, v[156:157] op_sel_hi:[1,0,1]
	v_pk_fma_f32 v[58:59], v[58:59], 0.5, v[158:159] op_sel_hi:[1,0,1]
	s_waitcnt vmcnt(29)
	v_pk_fma_f32 v[52:53], v[52:53], 0.5, v[160:161] op_sel_hi:[1,0,1]
	v_pk_fma_f32 v[54:55], v[54:55], 0.5, v[162:163] op_sel_hi:[1,0,1]
	s_waitcnt vmcnt(28)
	v_pk_fma_f32 v[48:49], v[48:49], 0.5, v[164:165] op_sel_hi:[1,0,1]
	v_pk_fma_f32 v[50:51], v[50:51], 0.5, v[166:167] op_sel_hi:[1,0,1]
	s_waitcnt vmcnt(27)
	v_pk_fma_f32 v[44:45], v[44:45], 0.5, v[168:169] op_sel_hi:[1,0,1]
	v_pk_fma_f32 v[46:47], v[46:47], 0.5, v[170:171] op_sel_hi:[1,0,1]
	s_waitcnt vmcnt(26)
	v_pk_fma_f32 v[40:41], v[40:41], 0.5, v[172:173] op_sel_hi:[1,0,1]
	v_pk_fma_f32 v[42:43], v[42:43], 0.5, v[174:175] op_sel_hi:[1,0,1]
	s_waitcnt vmcnt(25)
	v_pk_fma_f32 v[36:37], v[36:37], 0.5, v[176:177] op_sel_hi:[1,0,1]
	v_pk_fma_f32 v[38:39], v[38:39], 0.5, v[178:179] op_sel_hi:[1,0,1]
	s_waitcnt vmcnt(24)
	v_pk_fma_f32 v[32:33], v[32:33], 0.5, v[180:181] op_sel_hi:[1,0,1]
	v_pk_fma_f32 v[34:35], v[34:35], 0.5, v[182:183] op_sel_hi:[1,0,1]
	s_waitcnt vmcnt(23)
	v_pk_fma_f32 v[28:29], v[28:29], 0.5, v[186:187] op_sel_hi:[1,0,1]
	v_pk_fma_f32 v[30:31], v[30:31], 0.5, v[188:189] op_sel_hi:[1,0,1]
	s_waitcnt vmcnt(22)
	v_pk_fma_f32 v[24:25], v[24:25], 0.5, v[190:191] op_sel_hi:[1,0,1]
	v_pk_fma_f32 v[26:27], v[26:27], 0.5, v[192:193] op_sel_hi:[1,0,1]
	s_waitcnt vmcnt(21)
	v_pk_fma_f32 v[20:21], v[20:21], 0.5, v[194:195] op_sel_hi:[1,0,1]
	v_pk_fma_f32 v[22:23], v[22:23], 0.5, v[196:197] op_sel_hi:[1,0,1]
	s_waitcnt vmcnt(20)
	v_pk_fma_f32 v[16:17], v[16:17], 0.5, v[198:199] op_sel_hi:[1,0,1]
	v_pk_fma_f32 v[18:19], v[18:19], 0.5, v[200:201] op_sel_hi:[1,0,1]
	s_waitcnt vmcnt(19)
	v_pk_fma_f32 v[12:13], v[12:13], 0.5, v[202:203] op_sel_hi:[1,0,1]
	v_pk_fma_f32 v[14:15], v[14:15], 0.5, v[204:205] op_sel_hi:[1,0,1]
	s_waitcnt vmcnt(18)
	v_pk_fma_f32 v[8:9], v[8:9], 0.5, v[206:207] op_sel_hi:[1,0,1]
	v_pk_fma_f32 v[10:11], v[10:11], 0.5, v[208:209] op_sel_hi:[1,0,1]
	s_waitcnt vmcnt(17)
	v_pk_fma_f32 v[4:5], v[4:5], 0.5, v[210:211] op_sel_hi:[1,0,1]
	v_pk_fma_f32 v[6:7], v[6:7], 0.5, v[212:213] op_sel_hi:[1,0,1]
	s_waitcnt vmcnt(16)
	v_pk_fma_f32 v[0:1], v[0:1], 0.5, v[214:215] op_sel_hi:[1,0,1]
	v_pk_fma_f32 v[2:3], v[2:3], 0.5, v[216:217] op_sel_hi:[1,0,1]
	v_add_u32_e32 v219, 0x100000, v218
	global_store_dwordx4 v219, v[60:63], s[16:17]
	global_store_dwordx4 v219, v[56:59], s[16:17] offset:16
	global_store_dwordx4 v219, v[52:55], s[16:17] offset:512
	global_store_dwordx4 v219, v[48:51], s[16:17] offset:528
	v_add_u32_e32 v220, 0x120000, v218
	global_store_dwordx4 v220, v[44:47], s[16:17]
	global_store_dwordx4 v220, v[40:43], s[16:17] offset:16
	global_store_dwordx4 v220, v[36:39], s[16:17] offset:512
	global_store_dwordx4 v220, v[32:35], s[16:17] offset:528
	v_add_u32_e32 v219, 0x140000, v218
	global_store_dwordx4 v219, v[28:31], s[16:17]
	global_store_dwordx4 v219, v[24:27], s[16:17] offset:16
	global_store_dwordx4 v219, v[20:23], s[16:17] offset:512
	global_store_dwordx4 v219, v[16:19], s[16:17] offset:528
	v_add_u32_e32 v220, 0x160000, v218
	global_store_dwordx4 v220, v[12:15], s[16:17]
	global_store_dwordx4 v220, v[8:11], s[16:17] offset:16
	global_store_dwordx4 v220, v[4:7], s[16:17] offset:512
	global_store_dwordx4 v220, v[0:3], s[16:17] offset:528
	s_nop 1
	s_cbranch_vccnz .LBB0_1527
	s_andn2_b64 vcc, exec, s[12:13]
	s_cbranch_vccnz .LBB0_1526
	s_barrier
	s_branch .LBB0_1526
